# rwkv scan step loop: next-step LDS reads moved from right after the step barrier into the MFMA latency shadow; ring-slot address math moved before the barrier
# baseline (speedup 1.0000x reference)
; DI void rwkv_scan_phase(const Frame& F, int h, int vs) {
;     ...
;     } else if (w == 0) {
;         f32x4 Hf[4];
; #pragma unroll
;         for (int mt = 0; mt < 4; ++mt) Hf[mt] = (f32x4){0.f, 0.f, 0.f, 0.f};
;         __builtin_amdgcn_s_barrier();
;         f32x4 gqA[4], gqB[4]; u32x2 qqA[4], qqB[4]; bf16x8 pfA[4][2], pfB[4][2];
;     ...
;         SC_LDS(0, gqA, qqA, pfA);
.LBB0_812:
	s_and_b64 vcc, exec, s[0:1]
	s_mov_b32 s8, 0x4ad4a000
	s_cbranch_vccz .LBB0_815
	v_lshlrev_b32_e32 v132, 3, v128
	v_and_b32_e32 v129, 48, v129
	v_add_u32_e32 v12, 0, v132
	v_add_u32_e32 v20, 0, v129
	v_add_u32_e32 v21, v12, v132
	s_barrier
	ds_read_b128 v[8:11], v21
	ds_read_b128 v[0:3], v21 offset:1024
	ds_read_b128 v[52:55], v20 offset:10240
	ds_read_b128 v[44:47], v20 offset:10304
	ds_read_b128 v[16:19], v21 offset:2048
	ds_read_b128 v[4:7], v21 offset:3072
	ds_read2st64_b64 v[48:51], v12 offset0:16 offset1:17
	ds_read2st64_b64 v[24:27], v12 offset0:18 offset1:19
	ds_read_b128 v[28:31], v21 offset:4096
	ds_read_b128 v[12:15], v21 offset:5120
	ds_read_b128 v[40:43], v20 offset:10368
	ds_read_b128 v[32:35], v20 offset:10432
	ds_read_b128 v[36:39], v21 offset:6144
	ds_read_b128 v[20:23], v21 offset:7168
	v_lshlrev_b32_e32 v133, 4, v128
	s_mul_i32 s1, s6, 0xc100
	v_lshl_or_b32 v184, s9, 11, v133
	s_mul_hi_i32 s0, s6, 0xc100
	s_waitcnt lgkmcnt(0)
	s_add_u32 s4, s2, s1
	v_mov_b32_e32 v92, 0
	s_addc_u32 s5, s3, s0
	v_or_b32_e32 v130, 0x400, v184
	v_mov_b32_e32 v131, v185
	s_mov_b32 s0, -2
	v_mov_b32_e32 v93, v92
	v_mov_b32_e32 v94, v92
	v_mov_b32_e32 v95, v92
	v_mov_b32_e32 v124, v92
	v_mov_b32_e32 v125, v92
	v_mov_b32_e32 v126, v92
	v_mov_b32_e32 v127, v92
	v_mov_b32_e32 v120, v92
	v_mov_b32_e32 v121, v92
	v_mov_b32_e32 v122, v92
	v_mov_b32_e32 v123, v92
	v_mov_b32_e32 v116, v92
	v_mov_b32_e32 v117, v92
	v_mov_b32_e32 v118, v92
	v_mov_b32_e32 v119, v92
	s_movk_i32 s1, 0x2a00
	v_add_u32_e32 v56, s1, v129
	v_add_u32_e32 v57, s1, v132
	v_add_u32_e32 v58, s1, v133
; DI void rwkv_scan_phase(const Frame& F, int h, int vs) {
;     ...
;         SC_LDS(0, gqA, qqA, pfA);
;         for (int c = 0; c < NCH; c += 2) {
;             SC_STEP(c, gqA, qqA, pfA, gqB, qqB, pfB);
;             SC_STEP(c + 1, gqB, qqB, pfB, gqA, qqA, pfA);
;         }
.LBB0_814:
	v_lshlrev_b32_e32 v140, 16, v48
	v_and_b32_e32 v141, 0xffff0000, v48
	v_lshlrev_b32_e32 v48, 16, v49
	v_and_b32_e32 v49, 0xffff0000, v49
	v_pk_fma_f32 v[54:55], v[54:55], v[126:127], v[48:49]
	v_lshlrev_b32_e32 v48, 16, v50
	v_and_b32_e32 v49, 0xffff0000, v50
	v_pk_fma_f32 v[44:45], v[44:45], v[120:121], v[48:49]
	v_lshlrev_b32_e32 v48, 16, v24
	v_and_b32_e32 v49, 0xffff0000, v24
	v_lshlrev_b32_e32 v24, 16, v25
	v_and_b32_e32 v25, 0xffff0000, v25
	v_lshlrev_b32_e32 v50, 16, v51
	v_and_b32_e32 v51, 0xffff0000, v51
	v_pk_fma_f32 v[42:43], v[42:43], v[118:119], v[24:25]
	v_lshlrev_b32_e32 v24, 16, v26
	v_and_b32_e32 v25, 0xffff0000, v26
	v_lshlrev_b32_e32 v26, 16, v27
	v_and_b32_e32 v27, 0xffff0000, v27
	v_cvt_pk_bf16_f32 v134, v124, v125
	v_cvt_pk_bf16_f32 v135, v126, v127
	v_cvt_pk_bf16_f32 v136, v120, v121
	v_cvt_pk_bf16_f32 v137, v122, v123
	v_pk_fma_f32 v[52:53], v[52:53], v[124:125], v[140:141]
	v_pk_fma_f32 v[46:47], v[46:47], v[122:123], v[50:51]
	v_pk_fma_f32 v[40:41], v[40:41], v[116:117], v[48:49]
	v_pk_fma_f32 v[26:27], v[34:35], v[94:95], v[26:27]
	v_pk_fma_f32 v[24:25], v[32:33], v[92:93], v[24:25]
	v_mfma_f32_16x16x32_bf16 v[8:11], v[8:11], v[134:137], v[52:55]
	v_cvt_pk_bf16_f32 v138, v116, v117
	v_cvt_pk_bf16_f32 v139, v118, v119
	v_cvt_pk_bf16_f32 v140, v92, v93
	v_mfma_f32_16x16x32_bf16 v[16:19], v[16:19], v[134:137], v[44:47]
	v_cvt_pk_bf16_f32 v141, v94, v95
	v_lshl_add_u64 v[142:143], s[4:5], 0, v[184:185]
	v_lshl_add_u64 v[144:145], s[4:5], 0, v[130:131]
	v_mfma_f32_16x16x32_bf16 v[28:31], v[28:31], v[134:137], v[40:43]
	ds_read_b128 v[84:87], v58
	ds_read_b128 v[64:67], v58 offset:1024
	ds_read_b128 v[112:115], v56 offset:10240
	ds_read_b128 v[100:103], v56 offset:10304
	ds_read_b128 v[80:83], v58 offset:2048
	v_mfma_f32_16x16x32_bf16 v[24:27], v[36:39], v[134:137], v[24:27]
	ds_read_b128 v[68:71], v58 offset:3072
	ds_read2st64_b64 v[108:111], v57 offset0:16 offset1:17
	ds_read2st64_b64 v[88:91], v57 offset0:18 offset1:19
	ds_read_b128 v[76:79], v58 offset:4096
	ds_read_b128 v[60:63], v58 offset:5120
	v_mfma_f32_16x16x32_bf16 v[92:95], v[0:3], v[138:141], v[8:11]
	v_add_co_u32_e32 v0, vcc, s61, v142
	v_mfma_f32_16x16x32_bf16 v[116:119], v[4:7], v[138:141], v[16:19]
	s_nop 0
	v_addc_co_u32_e32 v1, vcc, 0, v143, vcc
	global_store_dwordx4 v[0:1], v[134:137], off
	ds_read_b128 v[104:107], v56 offset:10368
	ds_read_b128 v[96:99], v56 offset:10432
	ds_read_b128 v[72:75], v58 offset:6144
	ds_read_b128 v[56:59], v58 offset:7168
	v_mfma_f32_16x16x32_bf16 v[120:123], v[12:15], v[138:141], v[28:31]
	v_add_co_u32_e32 v0, vcc, s61, v144
	v_mfma_f32_16x16x32_bf16 v[124:127], v[20:23], v[138:141], v[24:27]
	s_nop 0
	v_addc_co_u32_e32 v1, vcc, 0, v145, vcc
	global_store_dwordx4 v[0:1], v[138:141], off
	s_add_i32 s1, s0, 4
	s_bfe_u32 s7, s1, 0xf0001
	s_mulk_i32 s7, 0x4925
	s_lshr_b32 s7, s7, 17
	s_mul_i32 s7, s7, 14
	s_sub_i32 s1, s1, s7
	s_and_b32 s1, s1, 0xffff
	s_mulk_i32 s1, 0x2a00
	s_add_i32 s1, s1, 0
	v_add_u32_e32 v20, s1, v129
	v_add_u32_e32 v12, s1, v132
	v_add_u32_e32 v21, s1, v133
	s_waitcnt lgkmcnt(0)
	s_barrier
	v_add_co_u32_e32 v142, vcc, s8, v142
	v_cvt_pk_bf16_f32 v134, v92, v93
	v_cvt_pk_bf16_f32 v135, v94, v95
	v_cvt_pk_bf16_f32 v136, v116, v117
	v_cvt_pk_bf16_f32 v137, v118, v119
	v_addc_co_u32_e32 v143, vcc, 0, v143, vcc
	global_store_dwordx4 v[142:143], v[134:137], off offset:2560
	v_add_co_u32_e32 v142, vcc, s8, v144
	v_cvt_pk_bf16_f32 v138, v120, v121
	v_cvt_pk_bf16_f32 v139, v122, v123
	v_cvt_pk_bf16_f32 v140, v124, v125
	v_cvt_pk_bf16_f32 v141, v126, v127
	v_addc_co_u32_e32 v143, vcc, 0, v145, vcc
	global_store_dwordx4 v[142:143], v[138:141], off offset:2560
	v_lshlrev_b32_e32 v142, 16, v108
	v_and_b32_e32 v143, 0xffff0000, v108
	v_lshlrev_b32_e32 v108, 16, v109
	v_and_b32_e32 v109, 0xffff0000, v109
	v_pk_fma_f32 v[94:95], v[114:115], v[94:95], v[108:109]
	v_lshlrev_b32_e32 v108, 16, v110
	v_and_b32_e32 v109, 0xffff0000, v110
	v_pk_fma_f32 v[100:101], v[100:101], v[116:117], v[108:109]
	v_lshlrev_b32_e32 v108, 16, v88
	v_and_b32_e32 v109, 0xffff0000, v88
	v_lshlrev_b32_e32 v88, 16, v89
	v_and_b32_e32 v89, 0xffff0000, v89
	v_lshlrev_b32_e32 v110, 16, v111
	v_and_b32_e32 v111, 0xffff0000, v111
	v_pk_fma_f32 v[106:107], v[106:107], v[122:123], v[88:89]
	v_lshlrev_b32_e32 v88, 16, v90
	v_and_b32_e32 v89, 0xffff0000, v90
	v_lshlrev_b32_e32 v90, 16, v91
	v_and_b32_e32 v91, 0xffff0000, v91
	v_pk_fma_f32 v[92:93], v[112:113], v[92:93], v[142:143]
	v_pk_fma_f32 v[102:103], v[102:103], v[118:119], v[110:111]
	v_pk_fma_f32 v[104:105], v[104:105], v[120:121], v[108:109]
	v_pk_fma_f32 v[90:91], v[98:99], v[126:127], v[90:91]
	v_pk_fma_f32 v[88:89], v[96:97], v[124:125], v[88:89]
	v_mfma_f32_16x16x32_bf16 v[84:87], v[84:87], v[134:137], v[92:95]
	ds_read_b128 v[8:11], v21
	ds_read_b128 v[0:3], v21 offset:1024
	ds_read_b128 v[52:55], v20 offset:10240
	ds_read_b128 v[44:47], v20 offset:10304
	v_mfma_f32_16x16x32_bf16 v[80:83], v[80:83], v[134:137], v[100:103]
	ds_read_b128 v[16:19], v21 offset:2048
	ds_read_b128 v[4:7], v21 offset:3072
	ds_read2st64_b64 v[48:51], v12 offset0:16 offset1:17
	ds_read2st64_b64 v[24:27], v12 offset0:18 offset1:19
	v_mfma_f32_16x16x32_bf16 v[76:79], v[76:79], v[134:137], v[104:107]
	ds_read_b128 v[28:31], v21 offset:4096
	ds_read_b128 v[12:15], v21 offset:5120
	ds_read_b128 v[40:43], v20 offset:10368
	v_mfma_f32_16x16x32_bf16 v[72:75], v[72:75], v[134:137], v[88:91]
	ds_read_b128 v[32:35], v20 offset:10432
	ds_read_b128 v[36:39], v21 offset:6144
	ds_read_b128 v[20:23], v21 offset:7168
	v_mfma_f32_16x16x32_bf16 v[124:127], v[64:67], v[138:141], v[84:87]
	v_mfma_f32_16x16x32_bf16 v[120:123], v[68:71], v[138:141], v[80:83]
	v_mfma_f32_16x16x32_bf16 v[116:119], v[60:63], v[138:141], v[76:79]
	v_mfma_f32_16x16x32_bf16 v[92:95], v[56:59], v[138:141], v[72:75]
	s_add_i32 s1, s0, 5
	s_bfe_u32 s7, s1, 0xf0001
	s_mulk_i32 s7, 0x4925
	s_lshr_b32 s7, s7, 17
	s_mul_i32 s7, s7, 14
	s_sub_i32 s1, s1, s7
	s_and_b32 s1, s1, 0xffff
	s_mulk_i32 s1, 0x2a00
	v_add_u32_e32 v56, s1, v129
	v_add_u32_e32 v57, s1, v132
	v_add_u32_e32 v58, s1, v133
	s_add_i32 s0, s0, 2
	s_waitcnt lgkmcnt(0)
	s_add_u32 s4, s4, 0xf1400
	s_addc_u32 s5, s5, 0
	s_cmpk_gt_u32 s0, 0xfd
	s_barrier
	s_cbranch_scc0 .LBB0_814
